# static s_setprio 1 for waves 4-7 (younger half) at GLA pass entry; covers GLA pass, combine and gla_light until the next GEMM's own flips
# speedup vs baseline: 1.0028x; 1.0028x over previous
; #define LAS __attribute__((address_space(3)))
; __device__ __forceinline__ int bid_() { int v = __builtin_amdgcn_readfirstlane((int)blockIdx.x); asm volatile("" : "+s"(v)); return v; }
; __device__ __forceinline__ int nblk_() { int v = __builtin_amdgcn_readfirstlane((int)gridDim.x); asm volatile("" : "+s"(v)); return v; }
; template <bool PASS2>
; __device__ __forceinline__ void gla_pass(LAS unsigned char* lds, const Params& p, int layer) {
;     ...
;     int tid = threadIdx.x; asm volatile("" : "+v"(tid));
;     const int wid = __builtin_amdgcn_readfirstlane(tid >> 6), lane = tid & 63, fr = lane & 15, fq = lane >> 4;
;     const int dk0 = (tid & 63) * 2;
;     bf16_t* P = (bf16_t*)(p.ws + OFF_PROJ);
;     const bf16_t* LR = (const bf16_t*)(p.ws + OFF_LR);
;     bf16_t* QT = (bf16_t*)(p.ws + OFF_E + (size_t)32 * 1024 * 1024);
;     bf16_t* O = (bf16_t*)(p.ws + OFF_O);
;     for (int item = bid_(); item < 256; item += nblk_()) {
;         const int b = item >> 7, h = (item >> 5) & 3, grp = item & 31;
; #pragma unroll 1
;         for (int dir = 0; dir < 2; ++dir) {
;             const int scan = (b * 4 + h) * 2 + dir;
;             bf16x8 wB1, wB2; float biasx;
;             { const float* Wc = (dir ? p.wdu_b : p.wdu_f) + (size_t)layer * 16 * 512 + h * 128 + wid * 16 + fr;
;               float wv[8]; unsigned h1[4], h2[4];
; #pragma unroll
;               for (int j = 0; j < 8; ++j) wv[j] = Wc[((fq & 1) * 8 + j) * 512];
; #pragma unroll
;               for (int jp = 0; jp < 4; ++jp) { const float a = wv[2 * jp], bq = wv[2 * jp + 1]; const unsigned hi = cvt_pk_bf16(a, bq);
;                   const unsigned lo = cvt_pk_bf16(a - bflo(hi), bq - bfhi(hi)); h1[jp] = hi; h2[jp] = fq < 2 ? lo : 0u; }
;               wB1 = __builtin_bit_cast(bf16x8, (u32x4){h1[0], h1[1], h1[2], h1[3]}); wB2 = __builtin_bit_cast(bf16x8, (u32x4){h2[0], h2[1], h2[2], h2[3]});
;               biasx = (dir ? p.bd_b : p.bd_f)[layer * 512 + h * 128 + wid * 16 + fr]; }
;     ...
;                 float tot0 = 0.f, tot1 = 0.f, offs0 = 0.f, offs1 = 0.f;
; #pragma unroll
;                 for (int s = 0; s < 8; ++s) { const f32x2 t2 = *(LAS f32x2*)(lds + SCOL + (s * 128 + dk0) * 4); tot0 += t2.x; tot1 += t2.y;
;                     const bool inc = dir == 0 ? (s < wid) : (s > wid); offs0 += inc ? t2.x : 0.f; offs1 += inc ? t2.y : 0.f; }
.LBB0_439:
	s_andn2_b64 vcc, exec, s[0:1]
	s_mov_b32 s30, s70
	s_cbranch_vccnz .LBB0_608
	v_readlane_b32 s0, v254, 34
	s_cmp_gt_i32 s0, 0
	s_mov_b64 s[0:1], -1
	s_cbranch_scc0 .LBB0_518
	v_writelane_b32 v254, s72, 35
	s_waitcnt vmcnt(0) lgkmcnt(0)
	v_mov_b32_e32 v1, v144
	s_cmpk_gt_i32 s60, 0xff
	v_writelane_b32 v254, s73, 36
	v_readfirstlane_b32 s0, v1
	s_cbranch_scc1 .LBB0_517
	v_readlane_b32 s6, v254, 25
	s_movk_i32 s1, 0x100
	v_readlane_b32 s7, v254, 26
	s_add_u32 s18, s6, 0x16200000
	v_cmp_gt_i32_e64 s[12:13], s1, v1
	s_movk_i32 s1, 0xff
	s_addc_u32 s19, s7, 0
	s_ashr_i32 s82, s0, 6
	s_cmp_lt_i32 s82, 4
	s_cbranch_scc1 .Lgla_prio_done
	s_setprio 1
.Lgla_prio_done:
	v_readlane_b32 s36, v254, 35
	v_cmp_lt_i32_e64 s[2:3], s1, v1
	v_readlane_b32 s37, v254, 36
	s_lshl_b32 s1, s82, 9
	v_writelane_b32 v254, s2, 37
	s_lshl_b32 s14, s82, 4
	v_lshlrev_b32_e32 v9, 4, v1
	v_writelane_b32 v254, s3, 38
	s_add_i32 s2, s1, 0
	v_and_b32_e32 v3, 63, v1
	s_lshl_b64 s[88:89], s[20:21], 15
	s_ashr_i32 s15, s14, 31
	v_and_b32_e32 v146, 0xf0, v9
	s_lshl_b32 s91, s82, 3
	s_add_i32 s2, s2, 0x1d200
	v_lshl_add_u64 v[118:119], s[36:37], 0, v[146:147]
	v_add_u32_e32 v185, 0, v146
	v_lshlrev_b32_e32 v146, 2, v3
	s_cmp_lt_u32 s0, 64
	v_lshl_add_u64 v[4:5], s[6:7], 0, v[146:147]
	s_mov_b64 s[4:5], 0x18600000
	s_cselect_b64 s[8:9], -1, 0
	s_ashr_i32 s1, s0, 3
	v_lshl_add_u64 v[122:123], v[4:5], 0, s[4:5]
	v_bfi_b32 v5, -16, s1, v1
	s_movk_i32 s34, 0x110
	v_lshlrev_b32_e32 v117, 1, v3
	v_cmp_gt_u32_e64 s[10:11], 32, v3
	v_lshlrev_b32_e32 v186, 3, v3
	s_lshl_b32 s4, s82, 5
	v_mul_lo_u32 v3, v5, s34
	s_movk_i32 s1, 0x90
	v_and_b32_e32 v10, 48, v1
	v_add_u32_e32 v12, 0, v3
	v_mul_lo_u32 v3, v5, s1
	s_add_i32 s1, 0, 0x11000
	s_ashr_i32 s5, s4, 31
	v_bfe_u32 v8, v1, 4, 2
	s_and_b32 s16, s4, 32
	v_add_u32_e32 v13, s1, v3
	s_add_i32 s30, 0, 0x14e00
	s_and_b32 s31, s0, 0xffffffc0
	v_add_u32_e32 v16, s1, v10
	s_lshl_b64 s[0:1], s[4:5], 1
	v_and_b32_e32 v116, 15, v1
	v_lshlrev_b32_e32 v2, 3, v8
	v_bfe_u32 v3, v1, 2, 2
	s_add_u32 s0, s6, s0
	v_lshlrev_b32_e32 v7, 3, v1
	v_or_b32_e32 v6, s4, v116
	v_or_b32_e32 v15, v2, v3
	s_addc_u32 s1, s7, s1
	v_mov_b32_e32 v3, v147
	v_add_u32_e32 v14, s30, v2
	v_and_b32_e32 v124, 24, v7
	v_lshl_add_u64 v[2:3], s[0:1], 0, v[2:3]
	s_mov_b64 s[0:1], 0x1a640000
	v_ashrrev_i32_e32 v7, 31, v6
	v_lshl_add_u64 v[126:127], v[2:3], 0, s[0:1]
	v_and_b32_e32 v2, 0xffffffc0, v9
	s_add_i32 s0, 0, 0x13400
	v_lshlrev_b64 v[130:131], 8, v[6:7]
	v_add_u32_e32 v7, 0x200, v1
	v_add_u32_e32 v3, s0, v2
	v_ashrrev_i32_e32 v188, 2, v1
	v_lshlrev_b32_e32 v2, 8, v1
	v_ashrrev_i32_e32 v189, 4, v1
	v_ashrrev_i32_e32 v190, 4, v7
	v_ashrrev_i32_e32 v193, 5, v1
	v_ashrrev_i32_e32 v194, 5, v7
	v_add_u32_e32 v7, 0x400, v1
	v_add_u32_e32 v1, 0x600, v1
	s_mul_i32 s0, s82, 0x420
	s_or_b32 s3, s91, 1
	v_ashrrev_i32_e32 v196, 5, v1
	v_add_lshl_u32 v1, s0, v117, 2
	s_mul_i32 s0, s3, 0x84
	s_add_i32 s1, s0, 0x84
	v_add_lshl_u32 v17, s1, v117, 2
	s_add_i32 s1, s0, 0x108
	v_add_lshl_u32 v18, s1, v117, 2
	s_add_i32 s1, s0, 0x18c
	v_add_lshl_u32 v19, s1, v117, 2
	s_add_i32 s1, s0, 0x210
	v_ashrrev_i32_e32 v195, 5, v7
	v_add_lshl_u32 v7, s0, v117, 2
	s_or_b32 s72, s91, 2
	s_or_b32 s73, s91, 3
	s_or_b32 s92, s91, 4
	s_or_b32 s93, s91, 5
	v_add_lshl_u32 v20, s1, v117, 2
	s_or_b32 s84, s91, 6
	s_add_i32 s1, s0, 0x294
	s_or_b32 s85, s91, 7
	s_addk_i32 s0, 0x318
	v_writelane_b32 v254, s18, 39
	s_cmp_gt_i32 s82, 0
	v_add_lshl_u32 v21, s1, v117, 2
	v_writelane_b32 v254, s19, 40
	v_add_lshl_u32 v22, s0, v117, 2
	s_cselect_b64 s[0:1], -1, 0
	v_writelane_b32 v254, s0, 41
	s_cmp_lt_i32 s82, 0
	v_lshl_or_b32 v0, s20, 9, v116
	v_writelane_b32 v254, s1, 42
	s_cselect_b64 s[0:1], -1, 0
	v_writelane_b32 v254, s0, 43
	s_cmp_gt_i32 s82, 1
	v_add_u32_e32 v125, s14, v0
	v_writelane_b32 v254, s1, 44
	s_cselect_b64 s[0:1], -1, 0
	v_writelane_b32 v254, s0, 45
	s_cmp_lt_i32 s82, 1
	v_lshlrev_b32_e32 v0, 2, v8
	v_writelane_b32 v254, s1, 46
	s_cselect_b64 s[0:1], -1, 0
	v_writelane_b32 v254, s0, 47
	s_cmp_gt_i32 s82, 2
	v_or_b32_e32 v29, s16, v0
	v_writelane_b32 v254, s1, 48
	s_cselect_b64 s[0:1], -1, 0
; template <bool PASS2>
; __device__ __forceinline__ void gla_pass(LAS unsigned char* lds, const Params& p, int layer) {
;     ...
;                 float tot0 = 0.f, tot1 = 0.f, offs0 = 0.f, offs1 = 0.f;
; #pragma unroll
;                 for (int s = 0; s < 8; ++s) { const f32x2 t2 = *(LAS f32x2*)(lds + SCOL + (s * 128 + dk0) * 4); tot0 += t2.x; tot1 += t2.y;
;                     const bool inc = dir == 0 ? (s < wid) : (s > wid); offs0 += inc ? t2.x : 0.f; offs1 += inc ? t2.y : 0.f; }
;                 const float etot0 = __expf(tot0), etot1 = __expf(tot1), eg0 = __expf(gtot0), eg1 = __expf(gtot1);
; #pragma unroll
;                 for (int e = 0; e < 8; ++e) { const int i = wid * 8 + e;
;                     const float ec0 = __expf(c0[e] + offs0), ec1 = __expf(c1[e] + offs1), inv0 = __builtin_amdgcn_rcpf(ec0), inv1 = __builtin_amdgcn_rcpf(ec1);
;                     const unsigned kw = *(LAS unsigned*)(lds + SK + i * 272 + dk0 * 2);
;                     const float k0 = bflo(kw), k1 = bfhi(kw);
;                     if (PASS2) { const unsigned qw = *(LAS unsigned*)(lds + SQ + i * 272 + dk0 * 2);
;                         const float qe0 = bflo(qw) * 0.08838834764831845f * ec0, qe1 = bfhi(qw) * 0.08838834764831845f * ec1;
;                         *(LAS unsigned*)(lds + SQ + i * 272 + dk0 * 2) = cvt_pk_bf16(qe0, qe1);
;                         const unsigned qt = cvt_pk_bf16(qe0 * eg0, qe1 * eg1);
;                         if (dir == 0) *(unsigned*)(QT + (size_t)(t0 + i) * 512 + h * 128 + dk0) = qt; else *(unsigned*)(P + (size_t)(t0 + i) * PW + h * 128 + dk0) = qt;
;                         *(LAS unsigned*)(lds + SK + i * 272 + dk0 * 2) = cvt_pk_bf16(k0 * inv0, k1 * inv1); }
;                 }
;                 if (wid == 0) { f32x2 t2; t2.x = etot0; t2.y = etot1; *(LAS f32x2*)(lds + SDEC + dk0 * 4) = t2; }
;                 gtot0 += tot0; gtot1 += tot1;
; #pragma unroll
;                 for (int it = 0; it < 4; ++it) { const int pi = tid + 512 * it, row = pi >> 5, seg = pi & 31;
;                     *(LAS u32x4*)(lds + SV + row * 528 + seg * 16) = rv[it]; }
;                 __syncthreads();
;                 if (PASS2) {
;                     f32x4 accP[2];
; #pragma unroll
;                     for (int s = 0; s < 2; ++s) { const int tt = wid * 2 + s, ib = tt >> 2, jb = tt & 3; f32x4 a = (f32x4){0.f, 0.f, 0.f, 0.f};
; #pragma unroll
	v_writelane_b32 v254, s0, 49
	s_cmp_lt_i32 s82, 2
	v_or_b32_e32 v30, 2, v29
	v_writelane_b32 v254, s1, 50
	s_cselect_b64 s[0:1], -1, 0
	v_writelane_b32 v254, s0, 51
	s_cmp_gt_i32 s82, 3
	v_cmp_gt_i32_e64 s[20:21], v30, v5
	v_writelane_b32 v254, s1, 52
	s_cselect_b64 s[0:1], -1, 0
	v_writelane_b32 v254, s0, 53
	s_cmp_lt_i32 s82, 3
	v_or_b32_e32 v30, 3, v29
	v_writelane_b32 v254, s1, 54
	s_cselect_b64 s[0:1], -1, 0
	v_writelane_b32 v254, s0, 55
	s_cmp_gt_i32 s82, 4
	v_cmp_gt_i32_e64 s[22:23], v30, v5
	v_writelane_b32 v254, s1, 56
	s_cselect_b64 s[0:1], -1, 0
	v_writelane_b32 v254, s0, 57
	s_cmp_lt_i32 s82, 4
	v_mul_lo_u32 v6, v6, s34
	v_writelane_b32 v254, s1, 58
	s_cselect_b64 s[0:1], -1, 0
	v_writelane_b32 v254, s0, 59
	s_cmp_gt_i32 s82, 5
	v_add_u32_e32 v187, 0, v146
	v_writelane_b32 v254, s1, 60
	s_cselect_b64 s[0:1], -1, 0
	v_writelane_b32 v254, s0, 61
	s_cmp_lt_i32 s82, 5
	v_lshl_add_u64 v[120:121], s[36:37], 0, v[146:147]
	v_writelane_b32 v254, s1, 62
	s_cselect_b64 s[0:1], -1, 0
	v_writelane_b32 v254, s0, 63
	s_cmp_gt_i32 s82, 6
	v_lshlrev_b32_e32 v146, 1, v124
	v_writelane_b32 v255, s1, 0
	s_cselect_b64 s[0:1], -1, 0
	v_writelane_b32 v255, s0, 1
	s_cmp_lt_i32 s82, 6
	v_add_u32_e32 v33, 0x1100, v6
	v_writelane_b32 v255, s1, 2
	s_cselect_b64 s[0:1], -1, 0
	s_cmp_gt_i32 s82, 7
	s_cselect_b64 s[6:7], -1, 0
	s_cmp_lt_i32 s82, 7
	s_cselect_b64 s[74:75], -1, 0
	s_or_b32 s4, s16, 16
	v_or_b32_e32 v30, s4, v0
	v_or_b32_e32 v31, 2, v30
	v_cmp_gt_i32_e64 s[28:29], v31, v5
	v_or_b32_e32 v31, 3, v30
	v_and_b32_e32 v4, 0x1f0, v9
	v_lshl_add_u64 v[128:129], s[18:19], 0, v[146:147]
	v_or_b32_e32 v27, s16, v116
	v_or_b32_e32 v28, s4, v116
	v_cmp_gt_i32_e64 s[16:17], v29, v5
	v_cmp_ge_i32_e64 s[18:19], v29, v5
	v_cmp_gt_i32_e64 s[24:25], v30, v5
	v_cmp_ge_i32_e64 s[26:27], v30, v5
	s_add_i32 s4, s31, 0
	v_add_u32_e32 v34, s30, v6
	v_add_u32_e32 v35, s30, v33
	v_add_u32_e32 v36, s30, v10
	v_mov_b32_e32 v37, s31
	v_add_u32_e32 v197, s30, v1
	v_add_u32_e32 v198, s30, v7
	v_add_u32_e32 v199, s30, v17
	v_add_u32_e32 v200, s30, v18
	v_add_u32_e32 v201, s30, v19
	v_add_u32_e32 v202, s30, v20
	v_add_u32_e32 v203, s30, v21
	v_add_u32_e32 v204, s30, v22
	v_cmp_gt_i32_e64 s[30:31], v31, v5
	v_mov_b32_e32 v5, v147
	v_add_u32_e32 v11, 0, v4
	v_mov_b32_e32 v32, s4
	v_lshl_add_u64 v[132:133], s[36:37], 0, v[4:5]
	v_lshlrev_b32_e32 v4, 6, v116
	s_mov_b32 s4, 0x13400
	s_movk_i32 s5, 0x210
	v_or3_b32 v208, v4, v10, s4
	v_mov_b32_e32 v4, s14
	v_writelane_b32 v255, s0, 3
	v_mad_u32_u24 v4, v8, s5, v4
	v_mad_u32_u24 v205, v15, s5, v32
	v_writelane_b32 v255, s1, 4
	v_mad_u32_u24 v207, v15, s34, 0
	v_or_b32_e32 v4, v4, v116
	v_mov_b32_e32 v5, 0x14e00
	s_movk_i32 s4, 0x840
	v_and_b32_e32 v9, 48, v9
	v_and_b32_e32 v2, 0x1000, v2
	v_mul_lo_u32 v23, v193, s5
	v_mul_lo_u32 v24, v194, s5
	v_mul_lo_u32 v25, v195, s5
	v_mul_lo_u32 v26, v196, s5
	v_mad_u32_u24 v27, v27, s34, 0
	v_mad_u32_u24 v28, v28, s34, 0
	v_lshlrev_b32_e32 v29, 1, v29
	v_lshlrev_b32_e32 v1, 1, v30
	v_add_u32_e32 v7, 0x4200, v205
	v_mul_u32_u24_e32 v17, 0x110, v116
	v_add_u32_e32 v206, 0, v10
	v_mul_u32_u24_e32 v18, 0x90, v116
	v_add_u32_e32 v15, 0x2200, v207
	v_lshl_add_u32 v209, v4, 2, v5
	v_mad_u32_u24 v4, v8, s4, v37
	v_writelane_b32 v255, s66, 5
	v_lshl_add_u32 v184, v116, 4, 0
	v_mul_lo_u32 v191, v189, s34
	v_mul_lo_u32 v192, v190, s34
	s_mulk_i32 s82, 0x880
	v_lshl_or_b32 v210, v116, 2, v4
	s_lshl_b64 s[76:77], s[14:15], 2
	v_lshlrev_b32_e32 v146, 2, v116
	v_lshlrev_b32_e32 v134, 2, v2
	v_add_u32_e32 v211, v3, v9
	v_add_u32_e32 v212, v11, v23
	v_add_u32_e32 v213, v11, v24
	v_add_u32_e32 v214, v11, v25
	v_add_u32_e32 v215, v11, v26
	v_add_u32_e32 v216, v27, v10
	v_add_u32_e32 v217, v12, v10
	v_add_u32_e32 v218, v28, v10
	v_add_u32_e32 v219, v13, v29
	v_add_u32_e32 v227, v13, v1
	v_add_u32_e32 v228, v14, v6
	v_add_u32_e32 v229, v7, v124
	v_add_u32_e32 v230, v34, v10
	v_add_u32_e32 v231, v36, v33
	v_add_u32_e32 v232, v35, v10
	v_add_u32_e32 v233, v15, v124
	v_lshlrev_b32_e32 v136, 1, v0
	v_add_u32_e32 v234, v206, v17
	v_add_u32_e32 v235, v16, v18
	v_writelane_b32 v255, s67, 6
	s_branch .LBB0_444
